# W_out and FF2 GEMMs: touch the f32 residual tile at the top of each unit so its HBM read overlaps the K loop
# baseline (speedup 1.0000x reference)
;     __device__ __forceinline__ bool next(int i, Unit& u) const { Unit t; if (!base.next(i >> 2, t)) return false; u.pm = t.pm; u.pn = (i & 3) * 4 + t.pn; return true; }
; template <class Epi, class Sched>
; __device__ __forceinline__ void gemm_phase(LAS unsigned char* lds, const Gemm g, const Sched& S, const Epi& E) {
;     ...
;     for (;;) {
;         const bool has_next = S.next(ui + 1, nxt);
;         const char* nA = has_next ? (const char*)g.A + (size_t)nxt.pm * tsA + (size_t)(nxt.pn >> g.a_sh) * pnA : cA; const char* nB = has_next ? (const char*)g.Bt + (size_t)nxt.pn * tsB : cB;
;     __device__ __forceinline__ void operator()(AccRef acc, const Unit& u, int wr, int wc, int fr, int fq) const {
;     ...
;                 const f32x4 n0 = *(const f32x4*)(xold + off) + a0, n1 = *(const f32x4*)(xold + off + 4) + a1;
.LBB0_1451:
	s_lshl_b32 s40, s36, 20
	s_lshl_b32 s41, s31, 10
	s_add_u32 s40, s40, s41
	v_lshrrev_b32_e32 v240, 1, v234
	v_and_b32_e32 v241, 1, v234
	v_lshlrev_b32_e32 v241, 9, v241
	v_lshl_add_u32 v240, v240, 12, v241
	v_add_u32_e32 v240, s40, v240
	s_waitcnt lgkmcnt(0)
	global_load_dword v242, v240, s[16:17]
	global_load_dword v242, v240, s[16:17] offset:128
	global_load_dword v242, v240, s[16:17] offset:256
	global_load_dword v242, v240, s[16:17] offset:384
	s_add_i32 s57, s57, 1
	s_mul_i32 s6, s57, s35
	s_mul_hi_u32 s7, s57, s34
	s_add_i32 s7, s7, s6
	s_mul_i32 s6, s57, s34
	s_add_u32 s40, s6, s2
	s_addc_u32 s41, s7, s3
	v_cmp_gt_i64_e32 vcc, s[40:41], v[222:223]
	v_cmp_lt_i64_e64 s[6:7], s[40:41], v[230:231]
	s_cbranch_vccnz .LBB0_1457
	s_ashr_i32 s41, s40, 31
	s_lshr_b32 s41, s41, 29
	s_add_i32 s46, s40, s41
	s_and_b32 s41, s46, -8
	s_sub_i32 s47, s40, s41
	s_cmp_gt_i32 s47, -1
	s_mov_b64 s[40:41], -1
	s_cbranch_scc0 .LBB0_1454
	s_lshl_b32 s61, s47, 6
	s_mov_b64 s[40:41], 0

;     __device__ __forceinline__ bool next(int i, Unit& u) const { Unit t; if (!base.next(i >> 2, t)) return false; u.pm = t.pm; u.pn = (i & 3) * 4 + t.pn; return true; }
; template <class Epi, class Sched>
; __device__ __forceinline__ void gemm_phase(LAS unsigned char* lds, const Gemm g, const Sched& S, const Epi& E) {
;     ...
;     for (;;) {
;         const bool has_next = S.next(ui + 1, nxt);
;         const char* nA = has_next ? (const char*)g.A + (size_t)nxt.pm * tsA + (size_t)(nxt.pn >> g.a_sh) * pnA : cA; const char* nB = has_next ? (const char*)g.Bt + (size_t)nxt.pn * tsB : cB;
;     __device__ __forceinline__ void operator()(AccRef acc, const Unit& u, int wr, int wc, int fr, int fq) const {
;     ...
;                 const f32x4 n0 = *(const f32x4*)(xold + off) + a0, n1 = *(const f32x4*)(xold + off + 4) + a1;
.LBB0_1633:
	s_lshl_b32 s0, s36, 20
	s_lshl_b32 s1, s31, 10
	s_add_u32 s0, s0, s1
	v_lshrrev_b32_e32 v240, 1, v234
	v_and_b32_e32 v241, 1, v234
	v_lshlrev_b32_e32 v241, 9, v241
	v_lshl_add_u32 v240, v240, 12, v241
	v_add_u32_e32 v240, s0, v240
	s_waitcnt lgkmcnt(0)
	global_load_dword v242, v240, s[18:19]
	global_load_dword v242, v240, s[18:19] offset:128
	global_load_dword v242, v240, s[18:19] offset:256
	global_load_dword v242, v240, s[18:19] offset:384
	s_add_i32 s58, s58, 1
	s_mul_i32 s0, s58, s35
	s_mul_hi_u32 s1, s58, s34
	s_add_i32 s1, s1, s0
	s_mul_i32 s0, s58, s34
	s_add_u32 s0, s0, s2
	s_addc_u32 s1, s1, s3
	v_cmp_gt_i64_e32 vcc, s[0:1], v[222:223]
	v_cmp_lt_i64_e64 s[6:7], s[0:1], v[230:231]
	s_cbranch_vccnz .LBB0_1639
	s_ashr_i32 s1, s0, 31
	s_lshr_b32 s1, s1, 29
	s_add_i32 s46, s0, s1
	s_and_b32 s1, s46, -8
	s_sub_i32 s47, s0, s1
	s_cmp_gt_i32 s47, -1
	s_mov_b64 s[0:1], -1
	s_cbranch_scc0 .LBB0_1636
	s_lshl_b32 s62, s47, 6
	s_mov_b64 s[0:1], 0
